# previous best plus backward copy propagation in both attention code paths (31 v_mov removed)
# baseline (speedup 1.0000x reference)
; #define LAS __attribute__((address_space(3)))
; __device__ __forceinline__ void attn_unit(LAS unsigned char* lds, const bf16_t* Qm, const bf16_t* Km, const bf16_t* VT, const bf16_t* GBm, bf16_t* YB, int b, int hp, int qb) {
;     ...
;         if (k0 < qw + 15 && !__all(Rs == 0.f)) {
;             f32x4 s[4];
; #pragma unroll
;             for (int rb = 0; rb < 4; ++rb) {
;                 const int c = rb >> 1, e = rb & 1;
;                 const int kl = 32 * c + (fr >> 2) * 8 + e * 4 + (fr & 3);
;                 s[rb] = (f32x4){0.f, 0.f, 0.f, 0.f};
; #pragma unroll
;                 for (int ks = 0; ks < 4; ++ks) {
;                     const bf16x8 a = *(const LAS bf16x8*)(KL + kl * 272 + (ks * 32 + fq * 8) * 2);
;                     s[rb] = __builtin_amdgcn_mfma_f32_16x16x32_bf16(a, qf[ks], s[rb], 0, 0, 0);
;                 }
;             }
;             const int qi = qw + fr;
;             float be[2][8], om[2][8];
; #pragma unroll
;             for (int c = 0; c < 2; ++c)
; #pragma unroll
;                 for (int i = 0; i < 8; ++i) {
;                     const float z = s[2 * c + (i >> 2)][i & 3];
;                     const int key = k0 + 32 * c + 8 * fq + i;
;                     const float e = __builtin_amdgcn_exp2f(-fabsf(z));
;                     const float r = __builtin_amdgcn_rcpf(1.0f + e);
;                     const bool pos = z >= 0.f, valid = key < qi;
;                     be[c][i] = valid ? (pos ? r : e * r) : 0.f;
;                     om[c][i] = valid ? (pos ? e * r : r) : 1.f;
.LBB0_519:
	s_add_i32 s12, s56, 64
	v_cmp_lt_u32_e32 vcc, s12, v109
	s_and_saveexec_b64 s[58:59], vcc
	s_cbranch_execz .LBB0_522
	v_cmp_eq_f32_e32 vcc, 0, v96
	s_cmp_eq_u64 vcc, exec
	s_cbranch_scc1 .LBB0_522
	v_readfirstlane_b32 s66, v109
	s_add_i32 s67, s12, 64
	s_nop 1
	s_sub_i32 s66, s66, 15
	s_cmp_le_u32 s67, s66
	s_cbranch_scc1 .Lattn_nomask
	ds_read_b128 v[120:123], v116
	ds_read_b128 v[124:127], v116 offset:64
	ds_read_b128 v[128:131], v116 offset:1088
	ds_read_b128 v[132:135], v116 offset:1152
	v_add_u32_e32 v99, s56, v108
	v_add_u32_e32 v103, 64, v99
	s_waitcnt lgkmcnt(3)
	v_mfma_f32_16x16x32_bf16 v[120:123], v[120:123], v[0:3], 0
	s_waitcnt lgkmcnt(2)
	v_mfma_f32_16x16x32_bf16 v[120:123], v[124:127], v[4:7], v[120:123]
	ds_read_b128 v[124:127], v116 offset:128
	ds_read_b128 v[136:139], v116 offset:192
	s_waitcnt lgkmcnt(3)
	v_mfma_f32_16x16x32_bf16 v[128:131], v[128:131], v[0:3], 0
	s_waitcnt lgkmcnt(1)
	v_mfma_f32_16x16x32_bf16 v[120:123], v[124:127], v[8:11], v[120:123]
	ds_read_b128 v[124:127], v116 offset:1216
	ds_read_b128 v[140:143], v116 offset:1280
	ds_read_b128 v[144:147], v116 offset:8704
	ds_read_b128 v[148:151], v116 offset:8768
	v_mfma_f32_16x16x32_bf16 v[128:131], v[132:135], v[4:7], v[128:131]
	ds_read_b128 v[132:135], v116 offset:8832
	ds_read_b128 v[152:155], v116 offset:8896
	ds_read_b128 v[156:159], v116 offset:9792
	ds_read_b128 v[160:163], v116 offset:9856
	s_waitcnt lgkmcnt(8)
	v_mfma_f32_16x16x32_bf16 v[120:123], v[136:139], v[12:15], v[120:123]
	ds_read_b128 v[136:139], v116 offset:9920
	ds_read_b128 v[164:167], v116 offset:9984
	s_waitcnt lgkmcnt(9)
	v_mfma_f32_16x16x32_bf16 v[124:127], v[124:127], v[8:11], v[128:131]
	s_nop 3
	v_exp_f32_e32 v97, v120
	s_nop 0
	v_add_f32_e32 v101, 1.0, v97
	s_waitcnt lgkmcnt(7)
	v_mfma_f32_16x16x32_bf16 v[128:131], v[144:147], v[0:3], 0
	v_rcp_f32_e32 v101, v101
	s_nop 0
	v_mul_f32_e32 v120, v97, v101
	s_waitcnt lgkmcnt(6)
	v_mfma_f32_16x16x32_bf16 v[128:131], v[148:151], v[4:7], v[128:131]
	v_mov_b32_e32 v97, v101
	v_cmp_lt_u32_e32 vcc, v103, v111
	v_mfma_f32_16x16x32_bf16 v[124:127], v[140:143], v[12:15], v[124:127]
	v_exp_f32_e32 v140, v121
	v_exp_f32_e32 v141, v122
	v_cndmask_b32_e32 v101, 0, v120, vcc
	s_waitcnt lgkmcnt(5)
	v_mfma_f32_16x16x32_bf16 v[128:131], v[132:135], v[8:11], v[128:131]
	v_add_f32_e32 v103, 1.0, v140
	v_rcp_f32_e32 v103, v103
	v_add_u32_e32 v120, 0x41, v99
	s_waitcnt lgkmcnt(3)
	v_mfma_f32_16x16x32_bf16 v[132:135], v[156:159], v[0:3], 0
	v_cmp_lt_u32_e64 s[12:13], v120, v111
	v_add_f32_e32 v120, 1.0, v141
	v_rcp_f32_e32 v120, v120
	s_waitcnt lgkmcnt(2)
	v_mfma_f32_16x16x32_bf16 v[132:135], v[160:163], v[4:7], v[132:135]
	v_cndmask_b32_e32 v97, 1.0, v97, vcc
	v_mul_f32_e32 v140, v140, v103
	s_waitcnt lgkmcnt(1)
	v_mfma_f32_16x16x32_bf16 v[132:135], v[136:139], v[8:11], v[132:135]
	v_exp_f32_e32 v136, v123
	v_exp_f32_e32 v137, v124
	v_cndmask_b32_e64 v142, 0, v140, s[12:13]
	v_add_u32_e32 v121, 0x42, v99
	v_mul_f32_e32 v140, v141, v120
	v_cndmask_b32_e64 v103, 1.0, v103, s[12:13]
	v_cmp_lt_u32_e64 s[12:13], v121, v111
	v_add_f32_e32 v121, 1.0, v136
	s_nop 0
	v_cndmask_b32_e64 v143, 0, v140, s[12:13]
	v_add_u32_e32 v122, 0x43, v99
	v_rcp_f32_e32 v121, v121
	v_cndmask_b32_e64 v120, 1.0, v120, s[12:13]
	v_cmp_lt_u32_e64 s[12:13], v122, v111
	v_add_f32_e32 v122, 1.0, v137
	v_rcp_f32_e32 v122, v122
	v_mul_f32_e32 v123, v136, v121
	v_mfma_f32_16x16x32_bf16 v[128:131], v[152:155], v[12:15], v[128:131]
	s_nop 0
	v_mul_f32_e32 v124, v137, v122
	v_exp_f32_e32 v137, v125
	v_cndmask_b32_e64 v144, 0, v123, s[12:13]
	v_add_u32_e32 v123, 0x44, v99
	v_cndmask_b32_e64 v121, 1.0, v121, s[12:13]
	v_cmp_lt_u32_e64 s[12:13], v123, v111
	v_add_f32_e32 v123, 1.0, v137
	v_rcp_f32_e32 v123, v123
	v_exp_f32_e32 v138, v128
	v_exp_f32_e32 v139, v131
	v_mul_f32_e32 v125, v137, v123
	v_exp_f32_e32 v137, v126
	v_cndmask_b32_e64 v145, 0, v124, s[12:13]
	v_add_u32_e32 v124, 0x45, v99
	v_cndmask_b32_e64 v122, 1.0, v122, s[12:13]
	v_cmp_lt_u32_e64 s[12:13], v124, v111
	v_add_f32_e32 v124, 1.0, v137
	v_rcp_f32_e32 v124, v124
	s_waitcnt lgkmcnt(0)
	v_mfma_f32_16x16x32_bf16 v[132:135], v[164:167], v[12:15], v[132:135]
	v_mul_f32_e32 v126, v137, v124
	v_exp_f32_e32 v137, v127
	v_cndmask_b32_e64 v146, 0, v125, s[12:13]
	v_add_u32_e32 v125, 0x46, v99
	v_cndmask_b32_e64 v123, 1.0, v123, s[12:13]
	v_cmp_lt_u32_e64 s[12:13], v125, v111
	v_add_f32_e32 v125, 1.0, v137
	v_add_u32_e32 v136, 0x47, v99
	v_cndmask_b32_e64 v126, 0, v126, s[12:13]
	v_rcp_f32_e32 v125, v125
	v_cndmask_b32_e64 v124, 1.0, v124, s[12:13]
	v_cmp_lt_u32_e64 s[12:13], v136, v111
	v_add_f32_e32 v136, 1.0, v138
	v_rcp_f32_e32 v136, v136
	v_mul_f32_e32 v127, v137, v125
	s_nop 1
	v_mul_f32_e32 v128, v138, v136
	v_exp_f32_e32 v138, v129
	v_cndmask_b32_e64 v147, 1.0, v125, s[12:13]
	v_add_u32_e32 v125, 0x60, v99
	v_cndmask_b32_e64 v127, 0, v127, s[12:13]
	v_cmp_lt_u32_e64 s[12:13], v125, v111
	v_add_f32_e32 v125, 1.0, v138
	v_rcp_f32_e32 v125, v125
	v_mul_f32_e32 v153, v147, v124
	v_mul_f32_e32 v154, v123, v153
	v_mul_f32_e32 v129, v138, v125
	v_exp_f32_e32 v138, v130
	v_cndmask_b32_e64 v140, 1.0, v136, s[12:13]
	v_add_u32_e32 v136, 0x61, v99
	v_cndmask_b32_e64 v128, 0, v128, s[12:13]
	v_cmp_lt_u32_e64 s[12:13], v136, v111
	v_add_f32_e32 v136, 1.0, v138
	v_add_u32_e32 v137, 0x62, v99
	v_cndmask_b32_e64 v129, 0, v129, s[12:13]
	v_rcp_f32_e32 v136, v136
	v_cndmask_b32_e64 v125, 1.0, v125, s[12:13]
	v_cmp_lt_u32_e64 s[12:13], v137, v111
	v_add_f32_e32 v137, 1.0, v139
	v_rcp_f32_e32 v137, v137
	v_mul_f32_e32 v130, v138, v136
	v_mul_f32_e32 v155, v122, v154
	v_mul_f32_e32 v156, v121, v155
	v_mul_f32_e32 v131, v139, v137
; #define LAS __attribute__((address_space(3)))
; __device__ __forceinline__ void attn_unit(LAS unsigned char* lds, const bf16_t* Qm, const bf16_t* Km, const bf16_t* VT, const bf16_t* GBm, bf16_t* YB, int b, int hp, int qb) {
;     ...
;             for (int c = 0; c < 2; ++c)
; #pragma unroll
;                 for (int i = 0; i < 8; ++i) {
;                     const float z = s[2 * c + (i >> 2)][i & 3];
;                     const int key = k0 + 32 * c + 8 * fq + i;
;                     const float e = __builtin_amdgcn_exp2f(-fabsf(z));
;                     const float r = __builtin_amdgcn_rcpf(1.0f + e);
;                     const bool pos = z >= 0.f, valid = key < qi;
;                     be[c][i] = valid ? (pos ? r : e * r) : 0.f;
;                     om[c][i] = valid ? (pos ? e * r : r) : 1.f;
;                 }
;             float suf[2][8], Gs[2], Tt[2];
; #pragma unroll
;             for (int c = 0; c < 2; ++c) {
;                 float run = 1.f;
; #pragma unroll
;                 for (int i = 7; i >= 0; --i) { suf[c][i] = run; run *= om[c][i]; }
;                 const float t1 = __shfl(run, (lane + 16) & 63), t2 = __shfl(run, (lane + 32) & 63), t3 = __shfl(run, (lane + 48) & 63);
;                 Gs[c] = (fq < 3 ? t1 : 1.f) * (fq < 2 ? t2 : 1.f) * (fq < 1 ? t3 : 1.f);
;                 Tt[c] = (run * t1) * (t2 * t3);
;             }
;             bf16x8 pf[2];
; #pragma unroll
;             for (int c = 0; c < 2; ++c) {
;                 const float basec = Rs * Gs[c] * (c == 0 ? Tt[1] : 1.f);
;                 float w[8];
; #pragma unroll
;                 for (int i = 0; i < 8; ++i) w[i] = be[c][i] * (suf[c][i] * basec);
;                 u32x4 pw; pw.x = cvt_pk_bf16(w[0], w[1]); pw.y = cvt_pk_bf16(w[2], w[3]); pw.z = cvt_pk_bf16(w[4], w[5]); pw.w = cvt_pk_bf16(w[6], w[7]);
;                 pf[c] = __builtin_bit_cast(bf16x8, pw);
;             }
;             Rs *= Tt[0] * Tt[1];
; #pragma unroll
;             for (int db = 0; db < 8; ++db)
; #pragma unroll
;                 for (int c = 0; c < 2; ++c) {
;                     const bf16x8 a = *(const LAS bf16x8*)(VL + (db * 16 + fr) * 144 + (32 * c + 8 * fq) * 2);
;                     o[db] = __builtin_amdgcn_mfma_f32_16x16x32_bf16(a, pf[c], o[db], 0, 0, 0);
;                 }
	v_exp_f32_e32 v139, v132
	v_cndmask_b32_e64 v141, 1.0, v136, s[12:13]
	v_add_u32_e32 v136, 0x63, v99
	v_cndmask_b32_e64 v130, 0, v130, s[12:13]
	v_cmp_lt_u32_e64 s[12:13], v136, v111
	v_add_f32_e32 v136, 1.0, v139
	v_rcp_f32_e32 v136, v136
	v_mul_f32_e32 v157, v120, v156
	v_mul_f32_e32 v103, v103, v157
	v_mul_f32_e32 v132, v139, v136
	v_exp_f32_e32 v139, v133
	v_cndmask_b32_e64 v148, 1.0, v137, s[12:13]
	v_add_u32_e32 v137, 0x64, v99
	v_cndmask_b32_e64 v131, 0, v131, s[12:13]
	v_cmp_lt_u32_e64 s[12:13], v137, v111
	v_add_f32_e32 v137, 1.0, v139
	v_rcp_f32_e32 v137, v137
	s_nop 1
	v_mul_f32_e32 v133, v139, v137
	v_exp_f32_e32 v139, v134
	v_cndmask_b32_e64 v149, 1.0, v136, s[12:13]
	v_add_u32_e32 v136, 0x65, v99
	v_cndmask_b32_e64 v132, 0, v132, s[12:13]
	v_cmp_lt_u32_e64 s[12:13], v136, v111
	v_add_f32_e32 v136, 1.0, v139
	v_rcp_f32_e32 v136, v136
	s_nop 1
	v_mul_f32_e32 v138, v139, v136
	v_exp_f32_e32 v139, v135
	v_cndmask_b32_e64 v150, 1.0, v137, s[12:13]
	v_add_u32_e32 v137, 0x66, v99
	v_cndmask_b32_e64 v133, 0, v133, s[12:13]
	v_cmp_lt_u32_e64 s[12:13], v137, v111
	v_add_f32_e32 v137, 1.0, v139
	v_rcp_f32_e32 v151, v137
	v_add_u32_e32 v99, 0x67, v99
	v_mul_f32_e32 v139, v139, v151
	v_cndmask_b32_e64 v134, 0, v138, s[12:13]
	v_cndmask_b32_e64 v152, 1.0, v136, s[12:13]
	v_cmp_lt_u32_e64 s[12:13], v99, v111
	v_mul_f32_e32 v136, v97, v103
	s_nop 0
	v_cndmask_b32_e64 v99, 0, v139, s[12:13]
	v_or_b32_e32 v135, v105, v107
	v_lshlrev_b32_e32 v135, 2, v135
	v_cndmask_b32_e64 v151, 1.0, v151, s[12:13]
	v_xor_b32_e32 v135, 0x80, v135
	v_mul_f32_e32 v152, v151, v152
	ds_bpermute_b32 v137, v135, v136
	ds_bpermute_b32 v138, v118, v136
	v_mul_f32_e32 v150, v150, v152
	v_mul_f32_e32 v149, v149, v150
	v_mul_f32_e32 v148, v148, v149
	v_mul_f32_e32 v158, v141, v148
	v_mul_f32_e32 v159, v125, v158
	ds_bpermute_b32 v139, v119, v136
	s_waitcnt lgkmcnt(2)
	v_cndmask_b32_e64 v97, 1.0, v137, s[10:11]
	s_waitcnt lgkmcnt(1)
	v_cndmask_b32_e64 v120, v138, 1.0, s[0:1]
	v_mul_f32_e32 v121, v140, v159
	v_mul_f32_e32 v97, v120, v97
	ds_bpermute_b32 v120, v135, v121
	ds_bpermute_b32 v123, v118, v121
	ds_bpermute_b32 v122, v119, v121
	s_waitcnt lgkmcnt(3)
	v_cndmask_b32_e64 v124, 1.0, v139, s[4:5]
	v_mul_f32_e32 v124, v97, v124
	s_waitcnt lgkmcnt(2)
	v_cndmask_b32_e64 v97, 1.0, v120, s[10:11]
	s_waitcnt lgkmcnt(1)
	v_cndmask_b32_e64 v125, v123, 1.0, s[0:1]
	v_mul_f32_e32 v97, v125, v97
	s_waitcnt lgkmcnt(0)
	v_cndmask_b32_e64 v125, 1.0, v122, s[4:5]
	v_pk_mul_f32 v[120:121], v[120:121], v[122:123]
	v_mul_f32_e32 v135, v97, v125
	v_mov_b32_e32 v97, v120
	v_mov_b32_e32 v125, v121
	v_pk_mul_f32 v[140:141], v[96:97], v[124:125]
	s_nop 0
	v_mul_f32_e32 v97, v140, v141
	v_mul_f32_e32 v120, v156, v97
	v_mul_f32_e32 v121, v143, v120
	v_mul_f32_e32 v120, v155, v97
	v_mul_f32_e32 v122, v144, v120
	v_mul_f32_e32 v120, v154, v97
	v_mul_f32_e32 v103, v103, v97
	v_mul_f32_e32 v123, v145, v120
	v_mul_f32_e32 v120, v153, v97
	v_mul_f32_e32 v101, v101, v103
	v_mul_f32_e32 v103, v157, v97
	v_mul_f32_e32 v124, v146, v120
	v_mul_f32_e32 v120, v147, v97
	v_mul_f32_e32 v97, v127, v97
	v_mul_f32_e32 v103, v142, v103
	v_mul_f32_e32 v125, v126, v120
	v_cvt_pk_bf16_f32 v120, v101, v103
	v_cvt_pk_bf16_f32 v121, v121, v122
	v_cvt_pk_bf16_f32 v122, v123, v124
	v_cvt_pk_bf16_f32 v123, v125, v97
	v_mul_f32_e32 v97, v96, v135
	v_mul_f32_e32 v124, v97, v148
	v_mul_f32_e32 v125, v130, v124
	v_mul_f32_e32 v124, v97, v149
	v_mul_f32_e32 v126, v131, v124
	v_mul_f32_e32 v124, v97, v150
	v_mul_f32_e32 v101, v97, v159
	v_mul_f32_e32 v127, v132, v124
	v_mul_f32_e32 v124, v97, v152
	v_mul_f32_e32 v101, v128, v101
	v_mul_f32_e32 v103, v97, v158
	v_mul_f32_e32 v128, v133, v124
	v_mul_f32_e32 v124, v151, v97
	v_mul_f32_e32 v103, v129, v103
	v_mul_f32_e32 v129, v134, v124
	v_mul_f32_e32 v97, v99, v97
	v_cvt_pk_bf16_f32 v124, v101, v103
	v_cvt_pk_bf16_f32 v125, v125, v126
	v_cvt_pk_bf16_f32 v126, v127, v128
	v_cvt_pk_bf16_f32 v127, v129, v97
	ds_read_b128 v[128:131], v117 offset:17408
	ds_read_b128 v[132:135], v117 offset:17472
	s_waitcnt lgkmcnt(1)
	v_mfma_f32_16x16x32_bf16 v[60:63], v[128:131], v[120:123], v[60:63]
	ds_read_b128 v[128:131], v117 offset:19712
	s_waitcnt lgkmcnt(1)
	v_mfma_f32_16x16x32_bf16 v[60:63], v[132:135], v[124:127], v[60:63]
	ds_read_b128 v[132:135], v117 offset:19776
	s_waitcnt lgkmcnt(1)
	v_mfma_f32_16x16x32_bf16 v[72:75], v[128:131], v[120:123], v[72:75]
	ds_read_b128 v[128:131], v117 offset:22016
	s_waitcnt lgkmcnt(1)
	v_mfma_f32_16x16x32_bf16 v[72:75], v[132:135], v[124:127], v[72:75]
	ds_read_b128 v[132:135], v117 offset:22080
	s_waitcnt lgkmcnt(1)
	v_mfma_f32_16x16x32_bf16 v[56:59], v[128:131], v[120:123], v[56:59]
	ds_read_b128 v[128:131], v117 offset:24320
	s_waitcnt lgkmcnt(1)
	v_mfma_f32_16x16x32_bf16 v[56:59], v[132:135], v[124:127], v[56:59]
	ds_read_b128 v[132:135], v117 offset:24384
	s_waitcnt lgkmcnt(1)
	v_mfma_f32_16x16x32_bf16 v[44:47], v[128:131], v[120:123], v[44:47]
	ds_read_b128 v[128:131], v117 offset:26624
	s_waitcnt lgkmcnt(1)
	v_mfma_f32_16x16x32_bf16 v[44:47], v[132:135], v[124:127], v[44:47]
	ds_read_b128 v[132:135], v117 offset:26688
	s_waitcnt lgkmcnt(1)
	v_mfma_f32_16x16x32_bf16 v[32:35], v[128:131], v[120:123], v[32:35]
	ds_read_b128 v[128:131], v117 offset:28928
	s_waitcnt lgkmcnt(1)
	v_mfma_f32_16x16x32_bf16 v[32:35], v[132:135], v[124:127], v[32:35]
	ds_read_b128 v[132:135], v117 offset:28992
	s_waitcnt lgkmcnt(1)
	v_mfma_f32_16x16x32_bf16 v[24:27], v[128:131], v[120:123], v[24:27]
	ds_read_b128 v[128:131], v117 offset:31232
	s_waitcnt lgkmcnt(1)
	v_mfma_f32_16x16x32_bf16 v[24:27], v[132:135], v[124:127], v[24:27]
	ds_read_b128 v[132:135], v117 offset:31296
	s_waitcnt lgkmcnt(1)
	v_mfma_f32_16x16x32_bf16 v[20:23], v[128:131], v[120:123], v[20:23]
	ds_read_b128 v[128:131], v117 offset:33536
	s_waitcnt lgkmcnt(1)
	v_mfma_f32_16x16x32_bf16 v[20:23], v[132:135], v[124:127], v[20:23]
	ds_read_b128 v[132:135], v117 offset:33600
	s_waitcnt lgkmcnt(1)
	v_mfma_f32_16x16x32_bf16 v[16:19], v[128:131], v[120:123], v[16:19]
	v_mul_f32_e64 v120, v136, v138
	v_mul_f32_e64 v121, v137, v139
	v_mul_f32_e32 v97, v120, v121
	s_waitcnt lgkmcnt(0)
	v_mfma_f32_16x16x32_bf16 v[16:19], v[132:135], v[124:127], v[16:19]
	v_mul_f32_e32 v97, v97, v141
	v_mul_f32_e32 v96, v96, v97
	s_branch .LBB0_522
; #define LAS __attribute__((address_space(3)))
; __device__ __forceinline__ void attn_unit(LAS unsigned char* lds, const bf16_t* Qm, const bf16_t* Km, const bf16_t* VT, const bf16_t* GBm, bf16_t* YB, int b, int hp, int qb) {
;     ...
;             for (int rb = 0; rb < 4; ++rb) {
;                 const int c = rb >> 1, e = rb & 1;
;                 const int kl = 32 * c + (fr >> 2) * 8 + e * 4 + (fr & 3);
;                 s[rb] = (f32x4){0.f, 0.f, 0.f, 0.f};
; #pragma unroll
;                 for (int ks = 0; ks < 4; ++ks) {
;                     const bf16x8 a = *(const LAS bf16x8*)(KL + kl * 272 + (ks * 32 + fq * 8) * 2);
;                     s[rb] = __builtin_amdgcn_mfma_f32_16x16x32_bf16(a, qf[ks], s[rb], 0, 0, 0);
;                 }
;             }
;             const int qi = qw + fr;
;             float be[2][8], om[2][8];
; #pragma unroll
;             for (int c = 0; c < 2; ++c)
; #pragma unroll
;                 for (int i = 0; i < 8; ++i) {
;                     const float z = s[2 * c + (i >> 2)][i & 3];
;                     const int key = k0 + 32 * c + 8 * fq + i;
;                     const float e = __builtin_amdgcn_exp2f(-fabsf(z));
;                     const float r = __builtin_amdgcn_rcpf(1.0f + e);
;                     const bool pos = z >= 0.f, valid = key < qi;
;                     be[c][i] = valid ? (pos ? r : e * r) : 0.f;
;                     om[c][i] = valid ? (pos ? e * r : r) : 1.f;
;                 }
;             float suf[2][8], Gs[2], Tt[2];
; #pragma unroll
;             for (int c = 0; c < 2; ++c) {
;                 float run = 1.f;
; #pragma unroll
;                 for (int i = 7; i >= 0; --i) { suf[c][i] = run; run *= om[c][i]; }
;                 const float t1 = __shfl(run, (lane + 16) & 63), t2 = __shfl(run, (lane + 32) & 63), t3 = __shfl(run, (lane + 48) & 63);
.Lattn_nomask:
	ds_read_b128 v[120:123], v116
	ds_read_b128 v[124:127], v116 offset:64
	ds_read_b128 v[128:131], v116 offset:1088
	ds_read_b128 v[132:135], v116 offset:1152
	v_add_u32_e32 v99, s56, v108
	s_waitcnt lgkmcnt(3)
	v_mfma_f32_16x16x32_bf16 v[120:123], v[120:123], v[0:3], 0
	s_waitcnt lgkmcnt(2)
	v_mfma_f32_16x16x32_bf16 v[120:123], v[124:127], v[4:7], v[120:123]
	ds_read_b128 v[124:127], v116 offset:128
	ds_read_b128 v[136:139], v116 offset:192
	s_waitcnt lgkmcnt(3)
	v_mfma_f32_16x16x32_bf16 v[128:131], v[128:131], v[0:3], 0
	s_waitcnt lgkmcnt(1)
	v_mfma_f32_16x16x32_bf16 v[120:123], v[124:127], v[8:11], v[120:123]
	ds_read_b128 v[124:127], v116 offset:1216
	ds_read_b128 v[140:143], v116 offset:1280
	ds_read_b128 v[144:147], v116 offset:8704
	ds_read_b128 v[148:151], v116 offset:8768
	v_mfma_f32_16x16x32_bf16 v[128:131], v[132:135], v[4:7], v[128:131]
	ds_read_b128 v[132:135], v116 offset:8832
	ds_read_b128 v[152:155], v116 offset:8896
	ds_read_b128 v[156:159], v116 offset:9792
	ds_read_b128 v[160:163], v116 offset:9856
	s_waitcnt lgkmcnt(8)
	v_mfma_f32_16x16x32_bf16 v[120:123], v[136:139], v[12:15], v[120:123]
	ds_read_b128 v[136:139], v116 offset:9920
	ds_read_b128 v[164:167], v116 offset:9984
	s_waitcnt lgkmcnt(9)
	v_mfma_f32_16x16x32_bf16 v[124:127], v[124:127], v[8:11], v[128:131]
	s_nop 3
	v_exp_f32_e32 v97, v120
	s_nop 0
	v_add_f32_e32 v101, 1.0, v97
	s_waitcnt lgkmcnt(7)
	v_mfma_f32_16x16x32_bf16 v[128:131], v[144:147], v[0:3], 0
	v_rcp_f32_e32 v101, v101
	s_nop 0
	v_mul_f32_e32 v120, v97, v101
	s_waitcnt lgkmcnt(6)
	v_mfma_f32_16x16x32_bf16 v[128:131], v[148:151], v[4:7], v[128:131]
	v_mov_b32_e32 v97, v101
	v_mfma_f32_16x16x32_bf16 v[124:127], v[140:143], v[12:15], v[124:127]
	v_exp_f32_e32 v140, v121
	v_exp_f32_e32 v141, v122
	v_mov_b32_e32 v101, v120
	s_waitcnt lgkmcnt(5)
	v_mfma_f32_16x16x32_bf16 v[128:131], v[132:135], v[8:11], v[128:131]
	v_add_f32_e32 v103, 1.0, v140
	v_rcp_f32_e32 v103, v103
	s_waitcnt lgkmcnt(3)
	v_mfma_f32_16x16x32_bf16 v[132:135], v[156:159], v[0:3], 0
	v_add_f32_e32 v120, 1.0, v141
	v_rcp_f32_e32 v120, v120
	s_waitcnt lgkmcnt(2)
	v_mfma_f32_16x16x32_bf16 v[132:135], v[160:163], v[4:7], v[132:135]
	v_mul_f32_e32 v142, v140, v103
	s_waitcnt lgkmcnt(1)
	v_mfma_f32_16x16x32_bf16 v[132:135], v[136:139], v[8:11], v[132:135]
	v_exp_f32_e32 v136, v123
	v_exp_f32_e32 v137, v124
	v_mul_f32_e32 v143, v141, v120
	v_add_f32_e32 v121, 1.0, v136
	v_rcp_f32_e32 v121, v121
	v_add_f32_e32 v122, 1.0, v137
	v_rcp_f32_e32 v122, v122
	v_mul_f32_e32 v144, v136, v121
	v_mfma_f32_16x16x32_bf16 v[128:131], v[152:155], v[12:15], v[128:131]
	s_nop 0
	v_mul_f32_e32 v145, v137, v122
	v_exp_f32_e32 v137, v125
	s_nop 0
	v_add_f32_e32 v123, 1.0, v137
	v_rcp_f32_e32 v123, v123
	s_nop 0
	s_nop 0
	v_exp_f32_e32 v138, v128
	v_exp_f32_e32 v139, v131
	v_mul_f32_e32 v146, v137, v123
	v_exp_f32_e32 v137, v126
	s_nop 0
	v_add_f32_e32 v124, 1.0, v137
	v_rcp_f32_e32 v124, v124
	s_waitcnt lgkmcnt(0)
	v_mfma_f32_16x16x32_bf16 v[132:135], v[164:167], v[12:15], v[132:135]
	v_mul_f32_e32 v126, v137, v124
	v_exp_f32_e32 v137, v127
	s_nop 0
	v_add_f32_e32 v125, 1.0, v137
	v_rcp_f32_e32 v125, v125
	v_add_f32_e32 v136, 1.0, v138
	v_rcp_f32_e32 v136, v136
	v_mul_f32_e32 v127, v137, v125
	s_nop 1
	v_mul_f32_e32 v128, v138, v136
	v_exp_f32_e32 v138, v129
	v_mov_b32_e32 v147, v125
	v_add_f32_e32 v125, 1.0, v138
	v_rcp_f32_e32 v125, v125
	v_mul_f32_e32 v153, v147, v124
	v_mul_f32_e32 v154, v123, v153
	v_mul_f32_e32 v129, v138, v125
	v_exp_f32_e32 v138, v130
	v_mov_b32_e32 v140, v136
	v_add_f32_e32 v136, 1.0, v138
	v_rcp_f32_e32 v136, v136
	v_add_f32_e32 v137, 1.0, v139
	v_rcp_f32_e32 v137, v137
	v_mul_f32_e32 v130, v138, v136
	v_mul_f32_e32 v155, v122, v154
	v_mul_f32_e32 v156, v121, v155
	v_mul_f32_e32 v131, v139, v137
	v_exp_f32_e32 v139, v132
	v_mov_b32_e32 v141, v136
	v_add_f32_e32 v136, 1.0, v139
	v_rcp_f32_e32 v136, v136
	v_mul_f32_e32 v157, v120, v156
	v_mul_f32_e32 v103, v103, v157
	v_mul_f32_e32 v132, v139, v136
	v_exp_f32_e32 v139, v133
	v_mov_b32_e32 v148, v137
	v_add_f32_e32 v137, 1.0, v139
	v_rcp_f32_e32 v137, v137
	s_nop 1
	v_mul_f32_e32 v133, v139, v137
	v_exp_f32_e32 v139, v134
	v_mov_b32_e32 v149, v136
	v_add_f32_e32 v136, 1.0, v139
	v_rcp_f32_e32 v136, v136
	s_nop 1
	v_mul_f32_e32 v134, v139, v136
	v_exp_f32_e32 v139, v135
	v_mov_b32_e32 v150, v137
	v_add_f32_e32 v137, 1.0, v139
	v_rcp_f32_e32 v151, v137
	s_nop 0
	v_mul_f32_e32 v99, v139, v151
	v_mov_b32_e32 v152, v136
	v_mul_f32_e32 v136, v97, v103
	v_or_b32_e32 v135, v105, v107
	v_lshlrev_b32_e32 v135, 2, v135
	v_xor_b32_e32 v135, 0x80, v135
	v_mul_f32_e32 v152, v151, v152
	ds_bpermute_b32 v137, v135, v136
	ds_bpermute_b32 v138, v118, v136
	v_mul_f32_e32 v150, v150, v152
	v_mul_f32_e32 v149, v149, v150
	v_mul_f32_e32 v148, v148, v149
	v_mul_f32_e32 v158, v141, v148
	v_mul_f32_e32 v159, v125, v158
	ds_bpermute_b32 v139, v119, v136
	s_waitcnt lgkmcnt(2)
; #define LAS __attribute__((address_space(3)))
; __device__ __forceinline__ unsigned cvt_pk_bf16(float lo, float hi) { unsigned r; asm volatile("v_cvt_pk_bf16_f32 %0, %1, %2" : "=v"(r) : "v"(lo), "v"(hi)); return r; }
; __device__ __forceinline__ void attn_unit(LAS unsigned char* lds, const bf16_t* Qm, const bf16_t* Km, const bf16_t* VT, const bf16_t* GBm, bf16_t* YB, int b, int hp, int qb) {
;     ...
;             float suf[2][8], Gs[2], Tt[2];
; #pragma unroll
;             for (int c = 0; c < 2; ++c) {
;                 float run = 1.f;
; #pragma unroll
;                 for (int i = 7; i >= 0; --i) { suf[c][i] = run; run *= om[c][i]; }
;                 const float t1 = __shfl(run, (lane + 16) & 63), t2 = __shfl(run, (lane + 32) & 63), t3 = __shfl(run, (lane + 48) & 63);
;                 Gs[c] = (fq < 3 ? t1 : 1.f) * (fq < 2 ? t2 : 1.f) * (fq < 1 ? t3 : 1.f);
;                 Tt[c] = (run * t1) * (t2 * t3);
;             }
;             bf16x8 pf[2];
; #pragma unroll
;             for (int c = 0; c < 2; ++c) {
;                 const float basec = Rs * Gs[c] * (c == 0 ? Tt[1] : 1.f);
;                 float w[8];
; #pragma unroll
;                 for (int i = 0; i < 8; ++i) w[i] = be[c][i] * (suf[c][i] * basec);
;                 u32x4 pw; pw.x = cvt_pk_bf16(w[0], w[1]); pw.y = cvt_pk_bf16(w[2], w[3]); pw.z = cvt_pk_bf16(w[4], w[5]); pw.w = cvt_pk_bf16(w[6], w[7]);
;                 pf[c] = __builtin_bit_cast(bf16x8, pw);
;             }
;             Rs *= Tt[0] * Tt[1];
; #pragma unroll
;             for (int db = 0; db < 8; ++db)
; #pragma unroll
;                 for (int c = 0; c < 2; ++c) {
;                     const bf16x8 a = *(const LAS bf16x8*)(VL + (db * 16 + fr) * 144 + (32 * c + 8 * fq) * 2);
;                     o[db] = __builtin_amdgcn_mfma_f32_16x16x32_bf16(a, pf[c], o[db], 0, 0, 0);
;                 }
	v_cndmask_b32_e64 v97, 1.0, v137, s[10:11]
	s_waitcnt lgkmcnt(1)
	v_cndmask_b32_e64 v120, v138, 1.0, s[0:1]
	v_mul_f32_e32 v121, v140, v159
	v_mul_f32_e32 v97, v120, v97
	ds_bpermute_b32 v120, v135, v121
	ds_bpermute_b32 v123, v118, v121
	ds_bpermute_b32 v122, v119, v121
	s_waitcnt lgkmcnt(3)
	v_cndmask_b32_e64 v124, 1.0, v139, s[4:5]
	v_mul_f32_e32 v124, v97, v124
	s_waitcnt lgkmcnt(2)
	v_cndmask_b32_e64 v97, 1.0, v120, s[10:11]
	s_waitcnt lgkmcnt(1)
	v_cndmask_b32_e64 v125, v123, 1.0, s[0:1]
	v_mul_f32_e32 v97, v125, v97
	s_waitcnt lgkmcnt(0)
	v_cndmask_b32_e64 v125, 1.0, v122, s[4:5]
	v_pk_mul_f32 v[120:121], v[120:121], v[122:123]
	v_mul_f32_e32 v135, v97, v125
	v_mov_b32_e32 v97, v120
	v_mov_b32_e32 v125, v121
	v_pk_mul_f32 v[140:141], v[96:97], v[124:125]
	s_nop 0
	v_mul_f32_e32 v97, v140, v141
	v_mul_f32_e32 v120, v156, v97
	v_mul_f32_e32 v121, v143, v120
	v_mul_f32_e32 v120, v155, v97
	v_mul_f32_e32 v122, v144, v120
	v_mul_f32_e32 v120, v154, v97
	v_mul_f32_e32 v103, v103, v97
	v_mul_f32_e32 v123, v145, v120
	v_mul_f32_e32 v120, v153, v97
	v_mul_f32_e32 v101, v101, v103
	v_mul_f32_e32 v103, v157, v97
	v_mul_f32_e32 v124, v146, v120
	v_mul_f32_e32 v120, v147, v97
	v_mul_f32_e32 v97, v127, v97
	v_mul_f32_e32 v103, v142, v103
	v_mul_f32_e32 v125, v126, v120
	v_cvt_pk_bf16_f32 v120, v101, v103
	v_cvt_pk_bf16_f32 v121, v121, v122
	v_cvt_pk_bf16_f32 v122, v123, v124
	v_cvt_pk_bf16_f32 v123, v125, v97
	v_mul_f32_e32 v97, v96, v135
	v_mul_f32_e32 v124, v97, v148
	v_mul_f32_e32 v125, v130, v124
	v_mul_f32_e32 v124, v97, v149
	v_mul_f32_e32 v126, v131, v124
	v_mul_f32_e32 v124, v97, v150
	v_mul_f32_e32 v101, v97, v159
	v_mul_f32_e32 v127, v132, v124
	v_mul_f32_e32 v124, v97, v152
	v_mul_f32_e32 v101, v128, v101
	v_mul_f32_e32 v103, v97, v158
	v_mul_f32_e32 v128, v133, v124
	v_mul_f32_e32 v124, v151, v97
	v_mul_f32_e32 v103, v129, v103
	v_mul_f32_e32 v129, v134, v124
	v_mul_f32_e32 v97, v99, v97
	v_cvt_pk_bf16_f32 v124, v101, v103
	v_cvt_pk_bf16_f32 v125, v125, v126
	v_cvt_pk_bf16_f32 v126, v127, v128
	v_cvt_pk_bf16_f32 v127, v129, v97
	ds_read_b128 v[128:131], v117 offset:17408
	ds_read_b128 v[132:135], v117 offset:17472
	s_waitcnt lgkmcnt(1)
	v_mfma_f32_16x16x32_bf16 v[60:63], v[128:131], v[120:123], v[60:63]
	ds_read_b128 v[128:131], v117 offset:19712
	s_waitcnt lgkmcnt(1)
	v_mfma_f32_16x16x32_bf16 v[60:63], v[132:135], v[124:127], v[60:63]
	ds_read_b128 v[132:135], v117 offset:19776
	s_waitcnt lgkmcnt(1)
	v_mfma_f32_16x16x32_bf16 v[72:75], v[128:131], v[120:123], v[72:75]
	ds_read_b128 v[128:131], v117 offset:22016
	s_waitcnt lgkmcnt(1)
	v_mfma_f32_16x16x32_bf16 v[72:75], v[132:135], v[124:127], v[72:75]
	ds_read_b128 v[132:135], v117 offset:22080
	s_waitcnt lgkmcnt(1)
	v_mfma_f32_16x16x32_bf16 v[56:59], v[128:131], v[120:123], v[56:59]
	ds_read_b128 v[128:131], v117 offset:24320
	s_waitcnt lgkmcnt(1)
	v_mfma_f32_16x16x32_bf16 v[56:59], v[132:135], v[124:127], v[56:59]
	ds_read_b128 v[132:135], v117 offset:24384
	s_waitcnt lgkmcnt(1)
	v_mfma_f32_16x16x32_bf16 v[44:47], v[128:131], v[120:123], v[44:47]
	ds_read_b128 v[128:131], v117 offset:26624
	s_waitcnt lgkmcnt(1)
	v_mfma_f32_16x16x32_bf16 v[44:47], v[132:135], v[124:127], v[44:47]
	ds_read_b128 v[132:135], v117 offset:26688
	s_waitcnt lgkmcnt(1)
	v_mfma_f32_16x16x32_bf16 v[32:35], v[128:131], v[120:123], v[32:35]
	ds_read_b128 v[128:131], v117 offset:28928
	s_waitcnt lgkmcnt(1)
	v_mfma_f32_16x16x32_bf16 v[32:35], v[132:135], v[124:127], v[32:35]
	ds_read_b128 v[132:135], v117 offset:28992
	s_waitcnt lgkmcnt(1)
	v_mfma_f32_16x16x32_bf16 v[24:27], v[128:131], v[120:123], v[24:27]
	ds_read_b128 v[128:131], v117 offset:31232
	s_waitcnt lgkmcnt(1)
	v_mfma_f32_16x16x32_bf16 v[24:27], v[132:135], v[124:127], v[24:27]
	ds_read_b128 v[132:135], v117 offset:31296
	s_waitcnt lgkmcnt(1)
	v_mfma_f32_16x16x32_bf16 v[20:23], v[128:131], v[120:123], v[20:23]
	ds_read_b128 v[128:131], v117 offset:33536
	s_waitcnt lgkmcnt(1)
	v_mfma_f32_16x16x32_bf16 v[20:23], v[132:135], v[124:127], v[20:23]
	ds_read_b128 v[132:135], v117 offset:33600
	s_waitcnt lgkmcnt(1)
	v_mfma_f32_16x16x32_bf16 v[16:19], v[128:131], v[120:123], v[16:19]
	v_mul_f32_e64 v120, v136, v138
	v_mul_f32_e64 v121, v137, v139
	v_mul_f32_e32 v97, v120, v121
	s_waitcnt lgkmcnt(0)
	v_mfma_f32_16x16x32_bf16 v[16:19], v[132:135], v[124:127], v[16:19]
	v_mul_f32_e32 v97, v97, v141
	v_mul_f32_e32 v96, v96, v97
